# prologue x-row pass: next row prefetched into shadow registers (counted vmcnt), global stores
# baseline (speedup 1.0000x reference)
; __device__ __forceinline__ unsigned pk2(float lo, float hi) { return pg8::cvt_pk_bf16(lo, hi); }
; __device__ __forceinline__ void x_row_to_bf16(const float* xrow, bf16* orow, float* rs, int lane) {
;     const int lo = lane & 31, hi = lane >> 5;
;     const f32x4* xr = (const f32x4*)xrow + 2 * lo + hi;
;     f32x4 v[8]; float s = 0.f;
; #pragma unroll
;     for (int j = 0; j < 8; ++j) { v[j] = xr[64 * j]; s += (v[j].x * v[j].x + v[j].y * v[j].y) + (v[j].z * v[j].z + v[j].w * v[j].w); }
;     const float rinv = 1.0f / sqrtf(wave_sum(s) * (1.f / DM) + EPS_RMS);
;     if (lane == 0) *rs = rinv;
; #pragma unroll
;     for (int i = 0; i < 4; ++i) { v2u wa, wb;
;         { const f32x4 x = v[2 * i]; wa.x = pk2(x.x, x.y); wa.y = pk2(x.z, x.w); }
;         { const f32x4 x = v[2 * i + 1]; wb.x = pk2(x.x, x.y); wb.y = pk2(x.z, x.w); }
;         const auto rx = __builtin_amdgcn_permlane32_swap(wa.x, wb.x, false, false);
;         const auto ry = __builtin_amdgcn_permlane32_swap(wa.y, wb.y, false, false);
;         v4u w16; w16.x = rx[0]; w16.y = ry[0]; w16.z = rx[1]; w16.w = ry[1];
;         *(v4u*)(orow + 256 * (2 * i + hi) + 8 * lo) = w16; }
; }
; __device__ __forceinline__ void p0_prologue(const Ptrs& P, LAS unsigned char* lds, int gw, int NGW, int wave, int lane) {
;     ...
;     for (int m = gw; m < M_TOK; m += NGW) x_row_to_bf16(P.x + (size_t)m * DM, P.XN + (size_t)m * DM, P.RS1 + m, lane);
.LBB0_86:
	s_cmpk_gt_i32 s60, 0x7fff
	s_cbranch_scc1 .LBB0_91
	v_mbcnt_lo_u32_b32 v2, -1, 0
	v_mbcnt_hi_u32_b32 v2, -1, v2
	v_and_b32_e32 v3, 64, v2
	v_add_u32_e32 v3, 64, v3
	v_xor_b32_e32 v4, 1, v2
	v_cmp_lt_i32_e32 vcc, v4, v3
	s_ashr_i32 s61, s60, 31
	s_lshl_b64 s[0:1], s[60:61], 2
	v_cndmask_b32_e32 v4, v2, v4, vcc
	v_lshlrev_b32_e32 v38, 2, v4
	v_xor_b32_e32 v4, 2, v2
	v_cmp_lt_i32_e32 vcc, v4, v3
	s_waitcnt lgkmcnt(0)
	s_add_u32 s40, s0, 0x700000
	s_addc_u32 s41, s1, 0
	v_cndmask_b32_e32 v4, v2, v4, vcc
	v_lshlrev_b32_e32 v39, 2, v4
	v_xor_b32_e32 v4, 4, v2
	v_cmp_lt_i32_e32 vcc, v4, v3
	s_lshl_b64 s[0:1], s[60:61], 13
	s_ashr_i32 s5, s4, 31
	v_cndmask_b32_e32 v4, v2, v4, vcc
	v_lshlrev_b32_e32 v40, 2, v4
	v_xor_b32_e32 v4, 8, v2
	v_cmp_lt_i32_e32 vcc, v4, v3
	v_cmp_eq_u32_e64 s[2:3], 63, v1
	s_lshl_b64 s[24:25], s[4:5], 2
	v_cndmask_b32_e32 v4, v2, v4, vcc
	v_lshlrev_b32_e32 v41, 2, v4
	v_xor_b32_e32 v4, 16, v2
	v_cmp_lt_i32_e32 vcc, v4, v3
	s_lshl_b64 s[26:27], s[4:5], 13
	v_mov_b32_e32 v44, 0x358637bd
	v_cndmask_b32_e32 v4, v2, v4, vcc
	v_lshlrev_b32_e32 v42, 2, v4
	v_xor_b32_e32 v4, 32, v2
	v_cmp_lt_i32_e32 vcc, v4, v3
	v_lshlrev_b32_e32 v3, 4, v67
	v_mov_b32_e32 v45, 0x260
	v_cndmask_b32_e32 v2, v2, v4, vcc
	v_and_b32_e32 v4, 31, v200
	v_lshlrev_b32_e32 v43, 2, v2
	v_lshlrev_b32_e32 v2, 5, v4
	v_or3_b32 v2, s0, v2, v3
	v_mov_b32_e32 v3, s1
	v_lshl_add_u64 v[2:3], s[36:37], 0, v[2:3]
	s_mov_b64 s[0:1], 0x1000
	v_lshl_add_u64 v[34:35], v[2:3], 0, s[0:1]
	s_lshl_b64 s[0:1], s[60:61], 12
	v_lshlrev_b32_e32 v2, 9, v67
	v_lshlrev_b32_e32 v3, 4, v4
	v_or3_b32 v36, s0, v2, v3
	v_mov_b32_e32 v37, s1
	s_lshl_b64 s[36:37], s[4:5], 12
	s_mov_b32 s5, 0xf800000
	s_mov_b32 s52, 0x6800000
	s_mov_b32 s53, s60
	global_load_dwordx4 v[154:157], v[34:35], off offset:-4096
	global_load_dwordx4 v[158:161], v[34:35], off offset:-3072
	global_load_dwordx4 v[146:149], v[34:35], off offset:-2048
	global_load_dwordx4 v[150:153], v[34:35], off offset:-1024
	global_load_dwordx4 v[138:141], v[34:35], off
	global_load_dwordx4 v[142:145], v[34:35], off offset:1024
	global_load_dwordx4 v[130:133], v[34:35], off offset:2048
	global_load_dwordx4 v[134:137], v[34:35], off offset:3072
	s_waitcnt vmcnt(0)
	s_branch .Lx_copy
.LBB0_88:
	s_or_b64 exec, exec, s[38:39]
	v_cvt_pk_bf16_f32 v26, v26, v27
	v_cvt_pk_bf16_f32 v27, v28, v29
	v_cvt_pk_bf16_f32 v28, v30, v31
	v_lshl_add_u64 v[30:31], s[62:63], 0, v[36:37]
	v_cvt_pk_bf16_f32 v29, v32, v33
	v_add_co_u32_e32 v30, vcc, s52, v30
	v_permlane32_swap_b32_e32 v26, v28
	v_permlane32_swap_b32_e32 v27, v29
	v_addc_co_u32_e32 v31, vcc, 0, v31, vcc
	global_store_dwordx4 v[30:31], v[26:29], off
	v_cvt_pk_bf16_f32 v18, v18, v19
	v_cvt_pk_bf16_f32 v19, v20, v21
	v_cvt_pk_bf16_f32 v20, v22, v23
	v_cvt_pk_bf16_f32 v21, v24, v25
	s_add_i32 s53, s53, s4
	v_permlane32_swap_b32_e32 v18, v20
	v_permlane32_swap_b32_e32 v19, v21
	global_store_dwordx4 v[30:31], v[18:21], off offset:1024
	v_cvt_pk_bf16_f32 v10, v10, v11
	v_cvt_pk_bf16_f32 v11, v12, v13
	v_cvt_pk_bf16_f32 v12, v14, v15
	v_cvt_pk_bf16_f32 v13, v16, v17
	s_add_u32 s40, s40, s24
	v_permlane32_swap_b32_e32 v10, v12
	v_permlane32_swap_b32_e32 v11, v13
	global_store_dwordx4 v[30:31], v[10:13], off offset:2048
	v_cvt_pk_bf16_f32 v2, v2, v3
	v_cvt_pk_bf16_f32 v3, v4, v5
	v_cvt_pk_bf16_f32 v4, v6, v7
	v_cvt_pk_bf16_f32 v5, v8, v9
	s_addc_u32 s41, s41, s25
	v_permlane32_swap_b32_e32 v2, v4
	v_permlane32_swap_b32_e32 v3, v5
	v_lshl_add_u64 v[34:35], v[34:35], 0, s[26:27]
	s_cmpk_gt_i32 s53, 0x7fff
	v_lshl_add_u64 v[36:37], v[36:37], 0, s[36:37]
	global_store_dwordx4 v[30:31], v[2:5], off offset:3072
	s_cbranch_scc1 .LBB0_91
.LBB0_89:
	s_waitcnt vmcnt(5)
; __device__ __forceinline__ void x_row_to_bf16(const float* xrow, bf16* orow, float* rs, int lane) {
;     const int lo = lane & 31, hi = lane >> 5;
;     const f32x4* xr = (const f32x4*)xrow + 2 * lo + hi;
;     f32x4 v[8]; float s = 0.f;
; #pragma unroll
;     for (int j = 0; j < 8; ++j) { v[j] = xr[64 * j]; s += (v[j].x * v[j].x + v[j].y * v[j].y) + (v[j].z * v[j].z + v[j].w * v[j].w); }
;     const float rinv = 1.0f / sqrtf(wave_sum(s) * (1.f / DM) + EPS_RMS);
;     if (lane == 0) *rs = rinv;
.Lx_copy:
	v_mov_b32_e32 v2, v130
	v_mov_b32_e32 v3, v131
	v_mov_b32_e32 v4, v132
	v_mov_b32_e32 v5, v133
	v_mov_b32_e32 v6, v134
	v_mov_b32_e32 v7, v135
	v_mov_b32_e32 v8, v136
	v_mov_b32_e32 v9, v137
	v_mov_b32_e32 v10, v138
	v_mov_b32_e32 v11, v139
	v_mov_b32_e32 v12, v140
	v_mov_b32_e32 v13, v141
	v_mov_b32_e32 v14, v142
	v_mov_b32_e32 v15, v143
	v_mov_b32_e32 v16, v144
	v_mov_b32_e32 v17, v145
	v_mov_b32_e32 v18, v146
	v_mov_b32_e32 v19, v147
	v_mov_b32_e32 v20, v148
	v_mov_b32_e32 v21, v149
	v_mov_b32_e32 v22, v150
	v_mov_b32_e32 v23, v151
	v_mov_b32_e32 v24, v152
	v_mov_b32_e32 v25, v153
	v_mov_b32_e32 v26, v154
	v_mov_b32_e32 v27, v155
	v_mov_b32_e32 v28, v156
	v_mov_b32_e32 v29, v157
	v_mov_b32_e32 v30, v158
	v_mov_b32_e32 v31, v159
	v_mov_b32_e32 v32, v160
	v_mov_b32_e32 v33, v161
	s_add_i32 s54, s53, s4
	s_cmpk_gt_i32 s54, 0x7fff
	s_cbranch_scc1 .Lx_nopf
	v_lshl_add_u64 v[162:163], v[34:35], 0, s[26:27]
	global_load_dwordx4 v[154:157], v[162:163], off offset:-4096
	global_load_dwordx4 v[158:161], v[162:163], off offset:-3072
	global_load_dwordx4 v[146:149], v[162:163], off offset:-2048
	global_load_dwordx4 v[150:153], v[162:163], off offset:-1024
	global_load_dwordx4 v[138:141], v[162:163], off
	global_load_dwordx4 v[142:145], v[162:163], off offset:1024
	global_load_dwordx4 v[130:133], v[162:163], off offset:2048
	global_load_dwordx4 v[134:137], v[162:163], off offset:3072
.Lx_nopf:
	v_mul_f32_e32 v46, v27, v27
	s_waitcnt lgkmcnt(0)
	v_mul_f32_e32 v47, v29, v29
	v_mul_f32_e32 v48, v31, v31
	v_mul_f32_e32 v49, v33, v33
	v_mul_f32_e32 v50, v19, v19
	v_mul_f32_e32 v51, v21, v21
	v_fmac_f32_e32 v46, v26, v26
	v_fmac_f32_e32 v47, v28, v28
	v_fmac_f32_e32 v48, v30, v30
	v_fmac_f32_e32 v49, v32, v32
	v_mul_f32_e32 v52, v23, v23
	v_mul_f32_e32 v53, v25, v25
	v_fmac_f32_e32 v50, v18, v18
	v_fmac_f32_e32 v51, v20, v20
	v_add_f32_e32 v46, v46, v47
	v_add_f32_e32 v47, v48, v49
	v_mul_f32_e32 v54, v11, v11
	v_mul_f32_e32 v55, v13, v13
	v_fmac_f32_e32 v52, v22, v22
	v_fmac_f32_e32 v53, v24, v24
	v_add_f32_e32 v48, v50, v51
	v_add_f32_e32 v46, v46, v47
	v_mul_f32_e32 v56, v15, v15
	v_mul_f32_e32 v57, v17, v17
	v_fmac_f32_e32 v54, v10, v10
	v_fmac_f32_e32 v55, v12, v12
	v_add_f32_e32 v49, v52, v53
	v_add_f32_e32 v46, v46, v48
	v_mul_f32_e32 v58, v3, v3
	v_mul_f32_e32 v59, v5, v5
	v_fmac_f32_e32 v56, v14, v14
	v_fmac_f32_e32 v57, v16, v16
	v_add_f32_e32 v50, v54, v55
	v_add_f32_e32 v46, v46, v49
	v_mul_f32_e32 v60, v7, v7
	v_mul_f32_e32 v61, v9, v9
	v_fmac_f32_e32 v58, v2, v2
	v_fmac_f32_e32 v59, v4, v4
	v_add_f32_e32 v51, v56, v57
	v_add_f32_e32 v46, v46, v50
	v_fmac_f32_e32 v60, v6, v6
	v_fmac_f32_e32 v61, v8, v8
	v_add_f32_e32 v52, v58, v59
	v_add_f32_e32 v46, v46, v51
	v_add_f32_e32 v46, v46, v52
	v_add_f32_e32 v47, v60, v61
	v_add_f32_e32 v46, v46, v47
	s_nop 1
	v_add_f32_dpp v46, v46, v46 quad_perm:[1,0,3,2] row_mask:0xf bank_mask:0xf
	s_nop 1
	v_add_f32_dpp v46, v46, v46 quad_perm:[2,3,0,1] row_mask:0xf bank_mask:0xf
	s_nop 1
	v_add_f32_dpp v46, v46, v46 row_half_mirror row_mask:0xf bank_mask:0xf
	s_nop 1
	v_add_f32_dpp v46, v46, v46 row_mirror row_mask:0xf bank_mask:0xf
	s_nop 1
	v_add_f32_dpp v46, v46, v46 row_bcast:15 row_mask:0xa bank_mask:0xf
	s_nop 1
	v_add_f32_dpp v46, v46, v46 row_bcast:31 row_mask:0xc bank_mask:0xf
	s_and_saveexec_b64 s[38:39], s[2:3]
	s_cbranch_execz .LBB0_88
	s_nop 1
	v_fmamk_f32 v46, v46, 0x3a000000, v44
	v_mul_f32_e32 v47, 0x4f800000, v46
	v_cmp_gt_f32_e32 vcc, s5, v46
	s_nop 1
	v_cndmask_b32_e32 v46, v46, v47, vcc
	v_sqrt_f32_e32 v47, v46
	s_nop 0
	v_add_u32_e32 v48, -1, v47
	v_fma_f32 v50, -v48, v47, v46
	v_add_u32_e32 v49, 1, v47
	v_cmp_ge_f32_e64 s[0:1], 0, v50
	s_nop 1
	v_cndmask_b32_e64 v48, v47, v48, s[0:1]
	v_fma_f32 v47, -v49, v47, v46
	v_cmp_lt_f32_e64 s[0:1], 0, v47
	s_nop 1
	v_cndmask_b32_e64 v47, v48, v49, s[0:1]
	v_mul_f32_e32 v48, 0x37800000, v47
	v_cndmask_b32_e32 v47, v47, v48, vcc
	v_cmp_class_f32_e32 vcc, v46, v45
	s_nop 1
	v_cndmask_b32_e32 v46, v47, v46, vcc
	v_div_scale_f32 v47, s[0:1], v46, v46, 1.0
	v_rcp_f32_e32 v48, v47
	s_add_u32 s0, s62, s40
	s_addc_u32 s1, s63, s41
	v_fma_f32 v49, -v47, v48, 1.0
	v_fmac_f32_e32 v48, v49, v48
	v_div_scale_f32 v49, vcc, 1.0, v46, 1.0
	v_mul_f32_e32 v50, v49, v48
	v_fma_f32 v51, -v47, v50, v49
	v_fmac_f32_e32 v50, v51, v48
	v_fma_f32 v47, -v47, v50, v49
	v_div_fmas_f32 v47, v47, v48, v50
	v_div_fixup_f32 v48, v47, v46, 1.0
	v_mov_b64_e32 v[46:47], s[0:1]
	global_store_dword v[46:47], v48, off
	s_branch .LBB0_88
